# static priority raise (s_setprio 1) for waves 4-7 inside the sequential HGRN chunk loop, reset at loop exit
# speedup vs baseline: 1.0032x; 1.0032x over previous
; __device__ __forceinline__ void hgrn_item(const Params& p, int layer, int bh, unsigned char* smem, int rep) {
;     ...
;     __syncthreads();
.LBB0_128:
	s_setprio 0
	s_waitcnt lgkmcnt(0)
	s_barrier

; #define HG_GLOAD(st_, ch_) do { const size_t co_ = (size_t)(ch_) * 4096; st_.q = *(const u32x4*)(gQS + co_); st_.k = *(const u32x4*)(gKDT + co_); st_.v = *(const u32x4*)(gVT + co_); \
;         st_.e = *(const f32x4*)(gEL + (size_t)(ch_) * 128); st_.o0 = gOI[(size_t)(ch_) * 1024]; st_.o1 = gOI[(size_t)(ch_) * 1024 + 64]; } while (0)
; #define HG_LSTORE(st_, buf_) do { unsigned char* lb_ = smem + (buf_) * 29696; *(u32x4*)((bf16_t*)lb_ + oq) = st_.q; *(u32x4*)((bf16_t*)(lb_ + 8704) + ok) = st_.k; *(u32x4*)((bf16_t*)(lb_ + 18944) + ok) = st_.v; \
;         if (tid < 32) *(f32x4*)((float*)(lb_ + 29184) + tid * 4) = st_.e; } while (0)
; __device__ __forceinline__ void hgrn_item(const Params& p, int layer, int bh, unsigned char* smem, int rep) {
;     ...
;     const bf16_t* gQS = (const bf16_t*)(p.ws + OFF_HQS) + (size_t)bh * 128 * 4096 + tid * 8;
;     const bf16_t* gKDT = (const bf16_t*)(p.ws + OFF_HKDT) + (size_t)bh * 128 * 4096 + tid * 8;
;     const bf16_t* gVT = (const bf16_t*)(p.ws + OFF_HVT) + (size_t)bh * 128 * 4096 + tid * 8;
;     const float* gEL = (const float*)(p.ws + OFF_HEL) + (size_t)bh * 128 * 128 + (tid & 31) * 4;
;     f32x4* gOI = (f32x4*)((unsigned char*)p.out + OUT_OI) + (size_t)bh * 128 * 1024 + w * 128 + lane;
;     f32x4* gOW = rep ? (f32x4*)(p.ws + OFF_GU) + (size_t)bh * 128 * 1024 + w * 128 + lane : gOI;
;     const int oq = (tid >> 4) * 136 + (tid & 15) * 8, ok = (tid >> 2) * 40 + (tid & 3) * 8;
;     f32x4 S[8];
; #pragma unroll
;     for (int kt = 0; kt < 8; ++kt) S[kt] = (f32x4){0.f, 0.f, 0.f, 0.f};
;     struct Stage { u32x4 q, k, v; f32x4 e, o0, o1; };
;     Stage sa, sb;
;     ...
;     f32x4 oc0, oc1;
;     HG_GLOAD(sa, 0); HG_LSTORE(sa, 0); oc0 = sa.o0; oc1 = sa.o1;
;     HG_GLOAD(sa, 1); HG_GLOAD(sb, 2);
;     __syncthreads();
;     ...
; #pragma unroll 1
;     for (int chn = 0; chn < 128; chn += 2) {
;         HG_BODY(chn, sa);
;         HG_BODY(chn + 1, sb);
;     }
.LBB0_226:
	s_or_b64 exec, exec, s[46:47]
	v_add_co_u32_e32 v0, vcc, 0x2000, v14
	v_and_b32_e32 v63, 15, v60
	s_nop 0
	v_addc_co_u32_e32 v1, vcc, 0, v15, vcc
	v_add_co_u32_e32 v4, vcc, 0x2000, v12
	v_lshl_or_b32 v65, v62, 4, v63
	s_nop 0
	v_addc_co_u32_e32 v5, vcc, 0, v13, vcc
	v_add_co_u32_e32 v8, vcc, 0x2000, v20
	global_load_dwordx4 v[0:3], v[0:1], off
	s_nop 0
	global_load_dwordx4 v[4:7], v[4:5], off
	v_addc_co_u32_e32 v9, vcc, 0, v21, vcc
	v_add_co_u32_e32 v16, vcc, 0x4000, v32
	global_load_dwordx4 v[8:11], v[8:9], off
	s_nop 0
	v_addc_co_u32_e32 v17, vcc, 0, v33, vcc
	v_add_co_u32_e32 v14, vcc, 0x4000, v14
	global_load_dwordx4 v[44:47], v[16:17], off
	global_load_dwordx4 v[40:43], v[16:17], off offset:1024
	v_addc_co_u32_e32 v15, vcc, 0, v15, vcc
	v_add_co_u32_e32 v16, vcc, 0x4000, v12
	v_lshrrev_b32_e32 v62, 1, v61
	s_nop 0
	v_addc_co_u32_e32 v17, vcc, 0, v13, vcc
	v_add_co_u32_e32 v20, vcc, 0x4000, v20
	global_load_dwordx4 v[12:15], v[14:15], off
	s_nop 0
	global_load_dwordx4 v[16:19], v[16:17], off
	v_addc_co_u32_e32 v21, vcc, 0, v21, vcc
	v_add_co_u32_e32 v36, vcc, 0x8000, v32
	global_load_dwordx4 v[20:23], v[20:21], off
	s_nop 0
	global_load_dwordx4 v[24:27], v[28:29], off offset:512
	s_nop 0
	global_load_dwordx4 v[28:31], v[28:29], off offset:1024
	v_addc_co_u32_e32 v37, vcc, 0, v33, vcc
	global_load_dwordx4 v[32:35], v[36:37], off
	s_nop 0
	global_load_dwordx4 v[36:39], v[36:37], off offset:1024
	v_and_b32_e32 v61, 48, v61
	v_and_b32_e32 v66, 24, v62
	v_add_u32_e32 v62, 0, v61
	s_movk_i32 s2, 0x50
	v_mad_u64_u32 v[96:97], s[8:9], v65, s2, v[62:63]
	v_lshl_add_u64 v[58:59], v[58:59], 4, s[44:45]
	v_readlane_b32 s8, v254, 57
	v_lshl_add_u64 v[58:59], v[58:59], 0, v[172:173]
	v_readlane_b32 s9, v254, 58
	v_mul_u32_u24_e32 v64, 0x110, v63
	v_and_b32_e32 v61, 48, v60
	v_lshl_add_u64 v[98:99], s[8:9], 0, v[58:59]
	v_and_b32_e32 v58, 31, v60
	v_mul_u32_u24_e32 v63, 0x50, v63
	v_lshlrev_b32_e32 v172, 4, v58
	v_lshl_add_u64 v[102:103], v[56:57], 1, s[0:1]
	v_mov_b32_e32 v56, 0
	v_add3_u32 v97, 0, v64, v66
	v_lshl_add_u64 v[100:101], s[42:43], 0, v[172:173]
	s_mov_b32 s2, -2
	v_add_u32_e32 v111, v62, v63
	v_add_u32_e32 v112, 0, v61
	v_mov_b32_e32 v57, v56
	v_mov_b32_e32 v58, v56
	v_mov_b32_e32 v59, v56
	v_mov_b32_e32 v60, v56
	v_mov_b32_e32 v61, v56
	v_mov_b32_e32 v62, v56
	v_mov_b32_e32 v63, v56
	v_mov_b32_e32 v64, v56
	v_mov_b32_e32 v65, v56
	v_mov_b32_e32 v66, v56
	v_mov_b32_e32 v67, v56
	v_mov_b32_e32 v68, v56
	v_mov_b32_e32 v69, v56
	v_mov_b32_e32 v70, v56
	v_mov_b32_e32 v71, v56
	v_mov_b32_e32 v72, v56
	v_mov_b32_e32 v73, v56
	v_mov_b32_e32 v74, v56
	v_mov_b32_e32 v75, v56
	v_mov_b32_e32 v76, v56
	v_mov_b32_e32 v77, v56
	v_mov_b32_e32 v78, v56
	v_mov_b32_e32 v79, v56
	v_mov_b32_e32 v84, v56
	v_mov_b32_e32 v85, v56
	v_mov_b32_e32 v86, v56
	v_mov_b32_e32 v87, v56
	v_mov_b32_e32 v80, v56
	v_mov_b32_e32 v81, v56
	v_mov_b32_e32 v82, v56
	v_mov_b32_e32 v83, v56
	s_waitcnt lgkmcnt(0)
	s_barrier
	v_lshrrev_b32_e32 v200, 6, v234
	s_nop 0
	v_readfirstlane_b32 s98, v200
	s_cmp_lt_u32 s98, 4
	s_cbranch_scc1 .Lhg_noprio
	s_setprio 1
.Lhg_noprio:
	s_branch .LBB0_228
.LBB0_227:
	s_mov_b64 s[8:9], 0x8000
	s_waitcnt lgkmcnt(0)
	s_barrier
	v_lshl_add_u64 v[98:99], v[98:99], 0, s[8:9]
	s_mov_b64 s[8:9], 0x400
	v_lshl_add_u64 v[100:101], v[100:101], 0, s[8:9]
	s_mov_b64 s[8:9], 0x4000
	s_waitcnt vmcnt(2)
	v_mov_b64_e32 v[40:41], v[92:93]
	v_mov_b64_e32 v[44:45], v[88:89]
	v_lshl_add_u64 v[102:103], v[102:103], 0, s[8:9]
	s_andn2_b64 vcc, exec, s[0:1]
	v_mov_b64_e32 v[42:43], v[94:95]
	v_mov_b64_e32 v[46:47], v[90:91]
	s_cbranch_vccz .LBB0_128
